# v25 + prologue weight transposes processed in reverse item order (last layer first) so the first layers' bf16 weights are the most recently written
# speedup vs baseline: 1.0032x; 1.0032x over previous
.LBB0_12:
	s_lshl_b32 s51, s66, 3
	s_lshl_b32 s92, s63, 3
	s_cmp_lt_i32 s90, 1
	s_cselect_b64 s[12:13], -1, 0
	s_cmp_gt_i32 s90, 0
	s_cselect_b64 s[4:5], -1, 0
	s_cmp_lt_i32 s91, 1
	s_cselect_b64 s[6:7], -1, 0
	s_or_b64 s[4:5], s[4:5], s[6:7]
	s_and_b64 vcc, exec, s[4:5]
	s_cbranch_vccnz .LBB0_105
	s_load_dwordx2 s[14:15], s[0:1], 0xf8
	v_readlane_b32 s2, v250, 0
	s_add_i32 s18, s2, s51
	s_cmp_gt_i32 s18, 0x165ff
	v_mbcnt_lo_u32_b32 v39, -1, 0
	v_mbcnt_hi_u32_b32 v39, -1, v39
	s_cbranch_scc1 .LBB0_69
	s_waitcnt lgkmcnt(0)
	s_add_u32 s19, s14, 0x16900000
	s_addc_u32 s20, s15, 0
	s_add_u32 s21, s14, 0x16600000
	s_addc_u32 s22, s15, 0
	s_add_u32 s23, s14, 0x10e00000
	s_addc_u32 s24, s15, 0
	s_add_u32 s25, s14, 0x5e00000
	s_addc_u32 s26, s15, 0
	s_add_u32 s27, s14, 0x3e00000
	s_addc_u32 s28, s15, 0
	s_add_u32 s29, s14, 0x24300000
	s_addc_u32 s30, s15, 0
	s_add_u32 s31, s14, 0x200000
	v_readlane_b32 s2, v250, 0
	v_lshlrev_b32_e32 v1, 3, v39
	s_addc_u32 s34, s15, 0
	s_lshl_b32 s2, s2, 14
	v_ashrrev_i32_e32 v0, 5, v39
	v_ashrrev_i32_e32 v41, 3, v39
	v_and_b32_e32 v6, 56, v1
	s_add_i32 s2, s2, 0
	v_and_b32_e32 v2, 31, v39
	v_mul_u32_u24_e32 v1, 0x84, v6
	v_lshlrev_b32_e32 v5, 2, v41
	v_add_u32_e32 v8, 4, v0
	v_add_u32_e32 v10, 8, v0
	v_add_u32_e32 v12, 12, v0
	v_add_u32_e32 v14, 16, v0
	v_add_u32_e32 v16, 20, v0
	v_add_u32_e32 v18, 24, v0
	v_add_u32_e32 v20, 28, v0
	v_mov_b32_e32 v3, 0
	v_lshl_add_u32 v4, v2, 2, s2
	s_movk_i32 s35, 0x84
	v_add3_u32 v42, s2, v1, v5
	v_add_u32_e32 v43, 8, v41
	v_add_u32_e32 v44, 16, v41
	v_add_u32_e32 v45, 24, v41
	v_mov_b32_e32 v1, v0
	v_mov_b32_e32 v5, v8
	v_mov_b32_e32 v7, v10
	v_mov_b32_e32 v9, v12
	v_mov_b32_e32 v11, v14
	v_mov_b32_e32 v13, v16
	v_mov_b32_e32 v15, v18
	v_mov_b32_e32 v17, v20
	s_add_i32 s36, 0, 0x23e68
	s_movk_i32 s37, 0x7fff
	s_mov_b32 s38, 0xffff0000
	s_add_i32 s39, 0, 0x23e58
	s_movk_i32 s40, 0xc00
	s_mov_b32 s41, 0x2aaaaaab
	s_movk_i32 s42, 0xc0
	s_movk_i32 s43, 0x7f
	s_add_i32 s44, 0, 0x23ee8
	s_movk_i32 s45, 0x2c00
	s_add_i32 s46, 0, 0x23ed0
	s_mov_b32 s47, 0xb000
	s_mov_b32 s48, 0x2e8ba2e9
	s_add_i32 s49, 0, 0x23e48
	s_mov_b64 s[4:5], 0x400000
	s_add_i32 s52, 0, 0x23e40
	s_movk_i32 s53, 0x3900
	v_lshlrev_b32_e32 v22, 2, v2
	v_mov_b32_e32 v46, 8
	s_sub_i32 s54, 0x165ff, s18
	s_branch .LBB0_16
.LBB0_15:
	s_sub_i32 s54, s54, s92
	s_cmp_lt_i32 s54, 0
	s_cbranch_scc1 .LBB0_69
